# P3->attention hand-over: thread-0 seam-arrive atomics moved behind the first attention unit's K/V/Q loads (they overlap), v161 merge without vmcnt(0); on top of v132
# speedup vs baseline: 1.0064x; 1.0064x over previous
; #define LAS __attribute__((address_space(3)))
; __device__ __forceinline__ unsigned xb_add(unsigned* p, unsigned v) { return __hip_atomic_fetch_add(p, v, __ATOMIC_RELAXED, __HIP_MEMORY_SCOPE_AGENT); }
; __device__ __forceinline__ void seam_arrive(unsigned* bar, unsigned x, volatile LAS unsigned* census) {
;     asm volatile("s_waitcnt vmcnt(0)" ::: "memory");
;     __syncthreads();
;     if (threadIdx.x == 0) {
;         __builtin_amdgcn_s_waitcnt(0);
;         const unsigned nloc = census[0], nx = census[1];
;         const unsigned old = xb_add(&bar[XB_XSUB(x)], 1u);
;         if (old + 1u == nloc) {
;             __builtin_amdgcn_fence(__ATOMIC_RELEASE, "agent");
;             asm volatile("s_waitcnt vmcnt(0)" ::: "memory");
;             const unsigned og = xb_add(&bar[XB_TOP], 1u);
;             if (og + 1u == nx) xb_add(&bar[XB_TOPGEN], 1u);
;         }
;     }
; }
; __device__ __forceinline__ void p2_mix(Frame& F, int slot) {
;     ...
;     if (F.tid == 0) F.MISC[16] = __hip_atomic_fetch_add(F.ctl + CW_ATTQ + 64 * F.dom, 1u, RLX_AGENT);
;     __syncthreads();
.LBB0_504:
	s_cmp_lg_u64 s[6:7], 0
	s_cselect_b64 s[8:9], -1, 0
	s_cmp_eq_u64 s[6:7], 0
	s_barrier
	s_cbranch_scc1 .LBB0_513
	s_waitcnt vmcnt(0)
	v_cmp_eq_u32_e32 vcc, 0, v0
	s_waitcnt vmcnt(0) lgkmcnt(0)
	s_barrier
.LBB0_513:
	v_cmp_eq_u32_e64 s[0:1], 0, v0
	s_and_saveexec_b64 s[2:3], s[0:1]
	s_cbranch_execz .LBB0_517
	s_mov_b64 s[14:15], exec
	s_waitcnt lgkmcnt(0)
	v_mbcnt_lo_u32_b32 v1, s14, 0
	v_mbcnt_hi_u32_b32 v1, s15, v1
	v_cmp_eq_u32_e32 vcc, 0, v1
	s_and_saveexec_b64 s[4:5], vcc
	s_cbranch_execz .LBB0_516
	s_lshl_b32 s16, s10, 6
	s_ashr_i32 s17, s16, 31
	s_lshl_b64 s[16:17], s[16:17], 2
	s_add_u32 s16, s30, s16
	s_addc_u32 s17, s31, s17
	s_bcnt1_i32_b64 s11, s[14:15]
	v_mov_b32_e32 v2, 0x8000
	v_mov_b32_e32 v3, s11
	global_atomic_add v2, v2, v3, s[16:17] sc0

; __device__ __forceinline__ void attn_issue(Frame& F, int id, KvRegs& R) {
;     const int b = id >> 5, n = (id >> 1) & 15, kvh = id & 1, key0 = 128 * (n - 1), tid = F.tid;
;     const bf16* Kb = (const bf16*)(F.ws + WS_K); const bf16* VT = (const bf16*)(F.ws + WS_VT);
;     const v4u zero4 = (v4u){0u, 0u, 0u, 0u};
; #pragma unroll
;     for (int i = 0; i < 6; ++i) { const int p = tid + 512 * i, row = p >> 3, pc = p & 7, pos = key0 + row;
;         R.k[i] = zero4; if (pos >= 0 && pos < SEQ) R.k[i] = *(const v4u*)(Kb + ((size_t)(b * SEQ + pos)) * 128 + kvh * 64 + pc * 8); }
; __device__ __forceinline__ void p2_mix(Frame& F, int slot) {
;     ...
;     __syncthreads();
;     int id = (int)F.MISC[16];
;     __syncthreads();
;     if (id < NU) att::attn_issue(F, base + id, R);
.LBB0_517:
	s_or_b64 exec, exec, s[2:3]
	s_add_i32 s2, 0, 0x22180
	s_waitcnt lgkmcnt(0)
	v_mov_b32_e32 v1, s2
	s_waitcnt vmcnt(0)
	s_barrier
	ds_read_b32 v1, v1
	s_movk_i32 s4, 0xff
	s_movk_i32 s2, 0x100
	s_lshl_b32 s11, s10, 8
	v_lshlrev_b32_e32 v8, 4, v0
	s_waitcnt lgkmcnt(0)
	v_cmp_lt_i32_e32 vcc, s4, v1
	v_readfirstlane_b32 s33, v1
	v_cmp_gt_i32_e64 s[2:3], s2, v1
	s_barrier
	s_cbranch_vccnz .LBB0_520
	s_add_i32 s4, s33, s11
	s_ashr_i32 s14, s4, 5
	s_lshl_b32 s4, s4, 6
	s_and_b32 s16, s4, 0x780
	s_and_b32 s15, s4, 64
	s_addk_i32 s16, 0xff80
	s_lshl_b32 s17, s14, 11
	s_lshl_b32 s4, s15, 1
	s_add_u32 s4, s30, s4
	s_addc_u32 s5, s31, 0
	v_and_b32_e32 v114, 0x70, v8
	v_mov_b32_e32 v115, 0
	v_lshl_add_u64 v[2:3], s[4:5], 0, v[114:115]
	s_mov_b64 s[4:5], 0x9000000
	s_cmpk_gt_u32 s16, 0x7ff
	v_lshl_add_u64 v[2:3], v[2:3], 0, s[4:5]
	s_cbranch_scc1 .LBB0_521
	v_lshrrev_b32_e32 v1, 3, v0
	v_or_b32_e32 v1, s16, v1
	v_or_b32_e32 v4, s17, v1
	v_ashrrev_i32_e32 v5, 31, v4
	v_lshlrev_b64 v[4:5], 8, v[4:5]
	v_lshl_add_u64 v[4:5], v[2:3], 0, v[4:5]
	global_load_dwordx4 v[114:117], v[4:5], off
	s_branch .LBB0_522
.LBB0_520:
	s_branch .LBB0_542
.LBB0_521:
	v_mov_b32_e32 v114, v115
	v_mov_b32_e32 v116, v115
	v_mov_b32_e32 v117, v115

; #define LAS __attribute__((address_space(3)))
; __device__ __forceinline__ unsigned xb_add(unsigned* p, unsigned v) { return __hip_atomic_fetch_add(p, v, __ATOMIC_RELAXED, __HIP_MEMORY_SCOPE_AGENT); }
; __device__ __forceinline__ void attn_issue(Frame& F, int id, KvRegs& R) {
;     ...
;     for (int i = 0; i < 6; ++i) { const int p = tid + 512 * i, d = p / 48, pc = p - d * 48, pos = key0 + pc * 8;
;         R.v[i] = zero4; if (pos >= 0 && pos < SEQ) R.v[i] = *(const v4u*)(VT + ((size_t)((b * 2 + kvh) * 64 + d)) * SEQ + pos); }
; __device__ __forceinline__ void seam_arrive(unsigned* bar, unsigned x, volatile LAS unsigned* census) {
;     asm volatile("s_waitcnt vmcnt(0)" ::: "memory");
;     __syncthreads();
;     if (threadIdx.x == 0) {
;         __builtin_amdgcn_s_waitcnt(0);
;         const unsigned nloc = census[0], nx = census[1];
;         const unsigned old = xb_add(&bar[XB_XSUB(x)], 1u);
;         if (old + 1u == nloc) {
;             __builtin_amdgcn_fence(__ATOMIC_RELEASE, "agent");
;             asm volatile("s_waitcnt vmcnt(0)" ::: "memory");
;             const unsigned og = xb_add(&bar[XB_TOP], 1u);
;             if (og + 1u == nx) xb_add(&bar[XB_TOPGEN], 1u);
;         }
;     }
; }
.LBB0_540:
	s_or_b64 exec, exec, s[14:15]
	v_mul_hi_u32 v3, v1, s18
	v_mad_i32_i24 v1, v3, s19, v1
	v_lshl_add_u32 v4, v1, 3, s16
	v_cmp_gt_u32_e32 vcc, s22, v4
	v_mov_b32_e32 v160, 0
	v_mov_b32_e32 v159, 0
	v_mov_b32_e32 v158, 0
	v_mov_b32_e32 v161, 0
	s_and_saveexec_b64 s[14:15], vcc
	s_cbranch_execz .LBB0_542
	v_add_u32_e32 v2, s17, v3
	v_ashrrev_i32_e32 v3, 31, v2
	v_lshlrev_b64 v[2:3], 12, v[2:3]
	v_lshl_add_u64 v[2:3], s[4:5], 0, v[2:3]
	v_mov_b32_e32 v5, 0
	v_lshl_add_u64 v[2:3], v[4:5], 1, v[2:3]
	global_load_dwordx4 v[158:161], v[2:3], off
.LBB0_542:
	s_or_b64 exec, exec, s[14:15]
	s_andn2_b64 vcc, exec, s[8:9]
	s_cbranch_vccnz .Lh1_skip
	s_mov_b64 s[48:49], s[2:3]
	v_cmp_eq_u32_e32 vcc, 0, v0
	s_nop 3
	s_and_saveexec_b64 s[0:1], vcc
	s_cbranch_execz .LBB0_512
	s_add_i32 s2, 0, 0x22168
	v_mov_b32_e32 v1, s2
	s_add_i32 s2, 0, 0x2216c
	s_waitcnt lgkmcnt(0)
	ds_read_b32 v2, v1
	v_mov_b32_e32 v1, s2
	s_lshl_b32 s2, s93, 8
	s_add_u32 s2, s6, s2
	s_addc_u32 s3, s7, 0
	v_mov_b32_e32 v3, 0x1000
	v_mov_b32_e32 v4, 1
	ds_read_b32 v1, v1
	global_atomic_add v3, v3, v4, s[2:3] offset:1024 sc0
	s_waitcnt vmcnt(0)
	v_add_u32_e32 v3, 1, v3
	s_waitcnt lgkmcnt(1)
	v_cmp_eq_u32_e32 vcc, v3, v2
	s_and_b64 exec, exec, vcc
	s_cbranch_execz .LBB0_512
	s_mov_b64 s[2:3], exec
	buffer_wbl2 sc1
	s_waitcnt lgkmcnt(0)
	s_waitcnt vmcnt(0)
	v_mbcnt_lo_u32_b32 v2, s2, 0
	v_mbcnt_hi_u32_b32 v2, s3, v2
	v_cmp_eq_u32_e32 vcc, 0, v2
	s_and_saveexec_b64 s[4:5], vcc
	s_cbranch_execz .LBB0_509
	s_bcnt1_i32_b64 s2, s[2:3]
	v_mov_b32_e32 v3, 0x3000
	v_mov_b32_e32 v4, s2
	global_atomic_add v3, v3, v4, s[6:7] offset:1024 sc0

; __device__ __forceinline__ unsigned xb_add(unsigned* p, unsigned v) { return __hip_atomic_fetch_add(p, v, __ATOMIC_RELAXED, __HIP_MEMORY_SCOPE_AGENT); }
; __device__ __forceinline__ void seam_arrive(unsigned* bar, unsigned x, volatile LAS unsigned* census) {
;     ...
;     if (threadIdx.x == 0) {
;         __builtin_amdgcn_s_waitcnt(0);
;         const unsigned nloc = census[0], nx = census[1];
;         const unsigned old = xb_add(&bar[XB_XSUB(x)], 1u);
;         if (old + 1u == nloc) {
;             __builtin_amdgcn_fence(__ATOMIC_RELEASE, "agent");
;             asm volatile("s_waitcnt vmcnt(0)" ::: "memory");
;             const unsigned og = xb_add(&bar[XB_TOP], 1u);
;             if (og + 1u == nx) xb_add(&bar[XB_TOPGEN], 1u);
;         }
;     }
.LBB0_512:
	s_or_b64 exec, exec, s[0:1]
	s_mov_b64 s[2:3], s[48:49]
	v_cmp_eq_u32_e64 s[0:1], 0, v0
	s_nop 3
.Lh1_skip:
	s_andn2_b64 vcc, exec, s[2:3]
	s_cbranch_vccnz .LBB0_580
